# lru_seq pass-1 loads batched; lru_pre conv window loads batched; RWKV scan vmcnt wait moved to sample path; weight conversion loads batched
# speedup vs baseline: 1.0174x; 1.0174x over previous
.LBB0_340:
	v_readlane_b32 s0, v252, 24
	v_readlane_b32 s4, v252, 0
	v_readlane_b32 s1, v252, 25
	v_mov_b32_e32 v0, v162
	v_readlane_b32 s5, v252, 1
	s_andn2_b64 vcc, exec, s[0:1]
	s_cbranch_vccnz .LBB0_369
	s_load_dwordx2 s[20:21], s[4:5], 0x158
	s_load_dwordx4 s[8:11], s[4:5], 0x80
	v_readlane_b32 s0, v251, 21
	v_readlane_b32 s1, v251, 22
	s_load_dwordx4 s[12:15], s[4:5], 0x58
	s_load_dwordx2 s[16:17], s[4:5], 0x70
	v_add_u32_e32 v2, s0, v0
	s_waitcnt lgkmcnt(0)
	s_add_u32 s0, s20, 0xe8c0000
	s_addc_u32 s1, s21, 0
	s_add_u32 s6, s20, 0x1c608000
	v_readlane_b32 s4, v250, 5
	s_addc_u32 s7, s21, 0
	v_readlane_b32 s5, v250, 6
	v_and_b32_e32 v56, 63, v0
	s_and_b64 s[4:5], s[4:5], exec
	v_and_b32_e32 v4, 15, v0
	v_ashrrev_i32_e32 v6, 3, v2
	v_lshl_add_u32 v57, v56, 2, 0
	v_lshlrev_b32_e32 v2, 1, v56
	v_readlane_b32 s4, v252, 26
	v_ashrrev_i32_e32 v5, 4, v0
	v_sub_u32_e32 v7, v57, v2
	v_or_b32_e32 v2, s4, v4
	v_mul_u32_u24_e32 v3, 0x90, v2
	v_lshlrev_b32_e32 v2, 3, v5
	v_and_b32_e32 v0, -16, v0
	s_cselect_b32 s28, 0x800, 0
	s_add_u32 s18, s20, 0x4bf8e00
	v_add3_u32 v58, 0, v3, v0
	v_ashrrev_i32_e32 v3, 31, v2
	s_addc_u32 s19, s21, 0
	v_lshl_add_u64 v[2:3], v[2:3], 1, s[20:21]
	s_mov_b64 s[20:21], 0x28c0000
	v_and_b32_e32 v18, -8, v6
	v_lshl_add_u64 v[20:21], v[2:3], 0, s[20:21]
	s_mov_b64 s[20:21], 0x28d0000
	v_lshl_add_u32 v24, v5, 2, s4
	s_movk_i32 s4, 0x90
	v_or_b32_e32 v0, 7, v6
	v_lshl_add_u64 v[22:23], v[2:3], 0, s[20:21]
	v_mul_lo_u32 v3, v18, s4
	v_mul_lo_u32 v13, v0, s4
	v_readlane_b32 s4, v252, 27
	v_lshlrev_b32_e32 v59, 8, v18
	v_or_b32_e32 v26, 1, v24
	v_or_b32_e32 v60, s4, v4
	v_or_b32_e32 v28, 2, v24
	v_or_b32_e32 v30, 3, v24
	v_or_b32_e32 v61, 16, v60
	v_or_b32_e32 v5, 0x100, v59
	v_or_b32_e32 v8, 0x200, v59
	v_or_b32_e32 v9, 0x300, v59
	v_or_b32_e32 v10, 0x400, v59
	v_or_b32_e32 v11, 0x500, v59
	v_or_b32_e32 v12, 0x600, v59
	v_lshlrev_b32_e32 v6, 8, v0
	v_lshlrev_b32_e32 v0, 6, v60
	v_lshl_add_u32 v4, v60, 2, 0
	v_cmp_eq_u32_e32 vcc, 0, v24
	v_lshlrev_b32_e32 v14, 8, v24
	v_lshlrev_b32_e32 v15, 8, v26
	v_lshlrev_b32_e32 v16, 8, v28
	v_lshlrev_b32_e32 v17, 8, v30
	v_lshlrev_b32_e32 v2, 6, v61
	v_readlane_b32 s4, v251, 34
	v_ashrrev_i32_e32 v19, 31, v18
	v_ashrrev_i32_e32 v25, 31, v24
	v_ashrrev_i32_e32 v27, 31, v26
	v_ashrrev_i32_e32 v29, 31, v28
	v_ashrrev_i32_e32 v31, 31, v30
	s_mov_b32 s71, s73
	v_add_u32_e32 v62, v7, v3
	v_add_u32_e32 v63, v57, v5
	v_add_u32_e32 v64, v57, v8
	v_add_u32_e32 v65, v57, v9
	v_add_u32_e32 v66, v57, v10
	v_add_u32_e32 v67, v57, v11
	v_add_u32_e32 v68, v57, v12
	v_add_u32_e32 v69, v57, v6
	v_add_u32_e32 v70, v7, v13
	v_lshlrev_b32_e32 v32, 1, v0
	s_xor_b64 s[20:21], vcc, -1
	v_lshlrev_b32_e32 v34, 1, v2
	v_add_u32_e32 v71, v4, v14
	v_add_u32_e32 v72, v4, v15
	v_add_u32_e32 v73, v4, v16
	v_add_u32_e32 v74, v4, v17
	s_mov_b32 s29, s4
	s_mov_b32 s98, 0
	v_writelane_b32 v250, s98, 40
	v_readlane_b32 s5, v251, 35
	s_branch .LBB0_343
.LBB0_342:
	s_or_b64 exec, exec, s[22:23]
	s_waitcnt vmcnt(0)
	v_add_f32_e32 v0, v6, v37
	v_mul_f32_e32 v0, 0xbfb8aa3b, v0
	v_exp_f32_e32 v0, v0
	v_add_f32_e32 v3, v3, v35
	v_mul_f32_e32 v3, 0xbfb8aa3b, v3
	ds_read_b32 v2, v71 offset:64
	v_add_f32_e32 v0, 1.0, v0
	v_exp_f32_e32 v3, v3
	v_rcp_f32_e32 v0, v0
	v_mad_u64_u32 v[46:47], s[4:5], v44, s49, 0
	v_add_f32_e32 v3, 1.0, v3
	s_waitcnt lgkmcnt(0)
	v_mul_f32_e32 v0, v0, v2
	v_rcp_f32_e32 v3, v3
	v_mul_f32_e32 v0, v75, v0
	v_mad_i32_i24 v47, v45, s49, v47
	v_bfe_u32 v2, v0, 16, 1
	v_add3_u32 v2, v0, v2, s78
	v_lshl_add_u64 v[44:45], s[0:1], 0, v[46:47]
	v_add_lshl_u32 v0, s30, v61, 1
	v_lshl_add_u64 v[44:45], v[44:45], 0, v[0:1]
	v_mul_f32_e32 v3, 0xc1000000, v3
	global_store_short_d16_hi v[44:45], v2, off
	v_bfe_u32 v2, v33, 16, 1
	v_lshl_add_u64 v[42:43], s[6:7], 0, v[42:43]
	v_mul_f32_e32 v6, v3, v36
	v_add3_u32 v2, v33, v2, s78
	v_lshl_add_u64 v[42:43], v[42:43], 0, v[0:1]
	v_add_f32_e32 v3, v6, v6
	global_store_short_d16_hi v[42:43], v2, off
	v_add_f32_e32 v2, v7, v37
	v_mul_f32_e32 v7, 0x3fb8aa3b, v3
	v_rndne_f32_e32 v7, v7
	v_fmamk_f32 v42, v7, 0xbf317218, v3
	v_fmac_f32_e32 v42, 0x3102e308, v7
	v_cmp_eq_f32_e32 vcc, s2, v7
	v_cvt_i32_f32_e32 v33, v7
	v_fmamk_f32 v7, v42, 0x395133b1, v171
	v_fmaak_f32 v7, v42, v7, 0x3c0887f9
	v_fmaak_f32 v7, v42, v7, 0x3d2aaa81
	v_fmaak_f32 v7, v42, v7, 0x3e2aaaab
	v_ldexp_f32 v33, 1.0, v33
	v_fma_f32 v7, v42, v7, 0.5
	v_cndmask_b32_e32 v33, v33, v178, vcc
	v_mul_f32_e32 v7, v42, v7
	v_fmac_f32_e32 v42, v42, v7
	v_add_f32_e32 v7, -1.0, v33
	v_fmac_f32_e32 v7, v33, v42
	v_add_f32_e32 v33, v7, v7
	v_cndmask_b32_e32 v7, v7, v33, vcc
	v_max_f32_e64 v7, -v7, 0
	v_cmp_gt_f32_e32 vcc, s93, v7
	v_mul_f32_e32 v33, 0x4f800000, v7
	v_mad_u64_u32 v[40:41], s[4:5], v50, s49, 0
	v_cndmask_b32_e32 v7, v7, v33, vcc
	v_sqrt_f32_e32 v33, v7
	v_mad_u64_u32 v[38:39], s[4:5], v52, s49, 0
	v_mad_u64_u32 v[16:17], s[4:5], v54, s49, 0
	v_add_u32_e32 v42, -1, v33
	v_fma_f32 v43, -v42, v33, v7
	v_cmp_ge_f32_e64 s[4:5], 0, v43
	v_add_u32_e32 v43, 1, v33
	v_mul_f32_e32 v2, 0xbfb8aa3b, v2
	v_cndmask_b32_e64 v42, v33, v42, s[4:5]
	v_fma_f32 v33, -v43, v33, v7
	v_cmp_lt_f32_e64 s[4:5], 0, v33
	v_exp_f32_e32 v2, v2
	v_mad_i32_i24 v41, v51, s49, v41
	v_cndmask_b32_e64 v33, v42, v43, s[4:5]
	v_mul_f32_e32 v42, 0x37800000, v33
	v_cndmask_b32_e32 v33, v33, v42, vcc
	v_cmp_class_f32_e32 vcc, v7, v170
	v_add_f32_e32 v2, 1.0, v2
	v_rcp_f32_e32 v2, v2
	v_cndmask_b32_e32 v7, v33, v7, vcc
	v_cmp_nlt_f32_e32 vcc, s3, v3
	s_mov_b32 s4, 0xc1000000
	v_mad_i32_i24 v39, v53, s49, v39
	v_cndmask_b32_e32 v7, 0, v7, vcc
	v_cmp_ngt_f32_e32 vcc, s52, v3
	v_mad_i32_i24 v17, v55, s49, v17
	s_add_i32 s29, s29, s46
	v_cndmask_b32_e32 v3, 1.0, v7, vcc
	ds_read_b32 v7, v72 offset:64
	s_waitcnt lgkmcnt(0)
	v_mul_f32_e32 v2, v2, v7
	v_mul_f32_e32 v2, v3, v2
	v_bfe_u32 v3, v2, 16, 1
	v_add3_u32 v7, v2, v3, s78
	v_lshl_add_u64 v[2:3], s[0:1], 0, v[40:41]
	v_lshl_add_u64 v[2:3], v[2:3], 0, v[0:1]
	global_store_short_d16_hi v[2:3], v7, off
	v_bfe_u32 v2, v6, 16, 1
	v_add3_u32 v6, v6, v2, s78
	v_lshl_add_u64 v[2:3], s[6:7], 0, v[10:11]
	v_lshl_add_u64 v[2:3], v[2:3], 0, v[0:1]
	global_store_short_d16_hi v[2:3], v6, off
	v_add_f32_e32 v2, v8, v37
	v_mul_f32_e32 v2, 0xbfb8aa3b, v2
	v_exp_f32_e32 v2, v2
	v_add_f32_e32 v3, v4, v35
	ds_read_b32 v4, v73 offset:64
	v_mul_f32_e32 v3, 0xbfb8aa3b, v3
	v_add_f32_e32 v2, 1.0, v2
	v_rcp_f32_e32 v2, v2
	v_exp_f32_e32 v3, v3
	v_lshl_add_u64 v[10:11], s[6:7], 0, v[14:15]
	v_lshl_add_u64 v[6:7], s[0:1], 0, v[38:39]
	s_waitcnt lgkmcnt(0)
	v_mul_f32_e32 v33, v2, v4
	v_add_f32_e32 v2, v9, v37
	v_mul_f32_e32 v2, 0xbfb8aa3b, v2
	v_exp_f32_e32 v2, v2
	v_add_f32_e32 v3, 1.0, v3
	v_rcp_f32_e32 v3, v3
	v_lshl_add_u64 v[6:7], v[6:7], 0, v[0:1]
	v_add_f32_e32 v2, 1.0, v2
	v_rcp_f32_e32 v4, v2
	v_add_f32_e32 v2, v5, v35
	v_mul_f32_e32 v2, 0xbfb8aa3b, v2
	v_exp_f32_e32 v2, v2
	v_lshl_add_u64 v[10:11], v[10:11], 0, v[0:1]
	v_add_f32_e32 v2, 1.0, v2
	v_rcp_f32_e32 v2, v2
	s_nop 0
	v_pk_mul_f32 v[2:3], v[2:3], s[4:5] op_sel_hi:[1,0]
	s_nop 0
	v_pk_mul_f32 v[2:3], v[2:3], v[36:37] op_sel_hi:[1,0]
	s_nop 0
	v_pk_add_f32 v[8:9], v[2:3], v[2:3]
	s_nop 0
	v_mul_f32_e32 v5, 0x3fb8aa3b, v9
	v_rndne_f32_e32 v5, v5
	v_fmamk_f32 v15, v5, 0xbf317218, v9
	v_fmac_f32_e32 v15, 0x3102e308, v5
	v_cmp_eq_f32_e32 vcc, s2, v5
	v_cvt_i32_f32_e32 v14, v5
	v_fmamk_f32 v5, v15, 0x395133b1, v171
	v_fmaak_f32 v5, v15, v5, 0x3c0887f9
	v_fmaak_f32 v5, v15, v5, 0x3d2aaa81
	v_fmaak_f32 v5, v15, v5, 0x3e2aaaab
	v_ldexp_f32 v14, 1.0, v14
	v_fma_f32 v5, v15, v5, 0.5
	v_cndmask_b32_e32 v14, v14, v178, vcc
	v_mul_f32_e32 v5, v15, v5
	v_fmac_f32_e32 v15, v15, v5
	v_add_f32_e32 v5, -1.0, v14
	v_fmac_f32_e32 v5, v14, v15
	v_add_f32_e32 v14, v5, v5
	v_cndmask_b32_e32 v5, v5, v14, vcc
	v_max_f32_e64 v5, -v5, 0
	v_cmp_gt_f32_e32 vcc, s93, v5
	v_mul_f32_e32 v14, 0x4f800000, v5
	s_nop 0
	v_cndmask_b32_e32 v5, v5, v14, vcc
	v_sqrt_f32_e32 v14, v5
	s_nop 0
	v_add_u32_e32 v15, -1, v14
	v_fma_f32 v35, -v15, v14, v5
	v_cmp_ge_f32_e64 s[4:5], 0, v35
	v_add_u32_e32 v35, 1, v14
	s_nop 0
	v_cndmask_b32_e64 v15, v14, v15, s[4:5]
	v_fma_f32 v14, -v35, v14, v5
	v_cmp_lt_f32_e64 s[4:5], 0, v14
	s_nop 1
	v_cndmask_b32_e64 v14, v15, v35, s[4:5]
	v_mul_f32_e32 v15, 0x37800000, v14
	v_cndmask_b32_e32 v14, v14, v15, vcc
	v_cmp_class_f32_e32 vcc, v5, v170
	s_nop 1
	v_cndmask_b32_e32 v5, v14, v5, vcc
	v_cmp_nlt_f32_e32 vcc, s3, v9
	s_nop 1
	v_cndmask_b32_e32 v5, 0, v5, vcc
	v_cmp_ngt_f32_e32 vcc, s52, v9
	s_nop 1
	v_cndmask_b32_e32 v5, 1.0, v5, vcc
	v_mul_f32_e32 v5, v5, v33
	v_bfe_u32 v9, v5, 16, 1
	v_add3_u32 v5, v5, v9, s78
	global_store_short_d16_hi v[6:7], v5, off
	v_bfe_u32 v5, v3, 16, 1
	v_add3_u32 v3, v3, v5, s78
	global_store_short_d16_hi v[10:11], v3, off
	v_mul_f32_e32 v3, 0x3fb8aa3b, v8
	v_rndne_f32_e32 v3, v3
	v_fmamk_f32 v6, v3, 0xbf317218, v8
	v_fmac_f32_e32 v6, 0x3102e308, v3
	v_cmp_eq_f32_e32 vcc, s2, v3
	v_cvt_i32_f32_e32 v5, v3
	v_fmamk_f32 v3, v6, 0x395133b1, v171
	v_fmaak_f32 v3, v6, v3, 0x3c0887f9
	v_fmaak_f32 v3, v6, v3, 0x3d2aaa81
	v_fmaak_f32 v3, v6, v3, 0x3e2aaaab
	v_ldexp_f32 v5, 1.0, v5
	v_fma_f32 v3, v6, v3, 0.5
	v_cndmask_b32_e32 v5, v5, v178, vcc
	v_mul_f32_e32 v3, v6, v3
	v_fmac_f32_e32 v6, v6, v3
	v_add_f32_e32 v3, -1.0, v5
	v_fmac_f32_e32 v3, v5, v6
	v_add_f32_e32 v5, v3, v3
	v_cndmask_b32_e32 v3, v3, v5, vcc
	v_max_f32_e64 v3, -v3, 0
	v_cmp_gt_f32_e32 vcc, s93, v3
	v_mul_f32_e32 v5, 0x4f800000, v3
	s_nop 0
	v_cndmask_b32_e32 v3, v3, v5, vcc
	v_sqrt_f32_e32 v5, v3
	s_nop 0
	v_add_u32_e32 v6, -1, v5
	v_fma_f32 v7, -v6, v5, v3
	v_cmp_ge_f32_e64 s[4:5], 0, v7
	v_add_u32_e32 v7, 1, v5
	s_nop 0
	v_cndmask_b32_e64 v6, v5, v6, s[4:5]
	v_fma_f32 v5, -v7, v5, v3
	v_cmp_lt_f32_e64 s[4:5], 0, v5
	s_nop 1
	v_cndmask_b32_e64 v5, v6, v7, s[4:5]
	v_mul_f32_e32 v6, 0x37800000, v5
	v_cndmask_b32_e32 v5, v5, v6, vcc
	v_cmp_class_f32_e32 vcc, v3, v170
	s_nop 1
	v_cndmask_b32_e32 v3, v5, v3, vcc
	ds_read_b32 v5, v74 offset:64
	v_cmp_nlt_f32_e32 vcc, s3, v8
	s_waitcnt lgkmcnt(0)
	v_mul_f32_e32 v4, v4, v5
	v_cndmask_b32_e32 v3, 0, v3, vcc
	v_cmp_ngt_f32_e32 vcc, s52, v8
	s_nop 1
	v_cndmask_b32_e32 v3, 1.0, v3, vcc
	v_mul_f32_e32 v3, v3, v4
	v_bfe_u32 v4, v3, 16, 1
	v_add3_u32 v3, v3, v4, s78
	v_lshl_add_u64 v[4:5], s[0:1], 0, v[16:17]
	v_lshl_add_u64 v[4:5], v[4:5], 0, v[0:1]
	global_store_short_d16_hi v[4:5], v3, off
	v_bfe_u32 v3, v2, 16, 1
	v_add3_u32 v4, v2, v3, s78
	v_lshl_add_u64 v[2:3], s[6:7], 0, v[12:13]
	v_lshl_add_u64 v[2:3], v[2:3], 0, v[0:1]
	global_store_short_d16_hi v[2:3], v4, off
	v_readlane_b32 s99, v250, 40
	v_readlane_b32 s98, v251, 34
	s_nop 0
	s_cmp_eq_u32 s99, 1
	s_cbranch_scc1 .LBB0_369
	s_movk_i32 s99, 0x800
	s_cmp_lg_u32 s46, 0x100
	s_cbranch_scc1 .Llru_pre_lim
	s_cmp_lt_u32 s98, 16
	s_cselect_b32 s99, 0x400, s99
.Llru_pre_lim:
	s_cmp_lt_i32 s29, s99
	s_cbranch_scc1 .LBB0_343
	s_cmp_lg_u32 s46, 0x100
	s_cbranch_scc1 .LBB0_369
	s_sub_u32 s99, s98, 16
	s_cmp_lt_u32 s99, 64
	s_cbranch_scc0 .LBB0_369
	s_lshr_b32 s29, s99, 4
	s_add_u32 s29, s29, 4
	s_lshl_b32 s29, s29, 8
	s_and_b32 s99, s99, 15
	s_or_b32 s29, s29, s99
	s_mov_b32 s99, 1
	v_writelane_b32 v250, s99, 40
	s_branch .LBB0_343
.LBB0_343:
	s_and_b32 s24, s29, 7
	s_lshl_b32 s30, s24, 6
	v_or_b32_e32 v4, s30, v56
	v_or_b32_e32 v0, s28, v4
	v_lshlrev_b32_e32 v0, 2, v0
	v_lshl_add_u64 v[2:3], s[12:13], 0, v[0:1]
	s_movk_i32 s4, 0x1000
	global_load_dword v7, v0, s[12:13]
	global_load_dword v6, v0, s[12:13] offset:2048
	v_add_co_u32_e32 v2, vcc, s4, v2
	v_or_b32_e32 v0, s70, v4
	s_nop 0
	v_addc_co_u32_e32 v3, vcc, 0, v3, vcc
	v_lshlrev_b32_e32 v0, 2, v0
	global_load_dword v10, v[2:3], off
	global_load_dword v8, v[2:3], off offset:2048
	global_load_dword v9, v0, s[14:15]
	s_ashr_i32 s4, s29, 3
	s_and_b32 s25, s4, 31
	s_ashr_i32 s5, s4, 31
	s_lshl_b64 s[22:23], s[4:5], 6
	v_lshl_add_u32 v12, s25, 6, v18
	v_lshlrev_b32_e32 v0, 1, v4
	v_lshl_add_u64 v[2:3], s[22:23], 0, v[18:19]
	v_lshl_add_u64 v[4:5], s[18:19], 0, v[0:1]
	s_barrier
	v_mad_u64_u32 v[14:15], s[26:27], v2, s79, v[4:5]
	v_mad_i32_i24 v15, v3, s79, v15
	s_mov_b32 s98, 0x2600
	s_mov_b32 s99, 0
	global_load_ushort v84, v[14:15], off
	v_lshl_add_u64 v[14:15], v[14:15], 0, s[98:99]
	global_load_ushort v85, v[14:15], off
	v_lshl_add_u64 v[14:15], v[14:15], 0, s[98:99]
	global_load_ushort v86, v[14:15], off
	v_lshl_add_u64 v[14:15], v[14:15], 0, s[98:99]
	global_load_ushort v87, v[14:15], off
	v_lshl_add_u64 v[14:15], v[14:15], 0, s[98:99]
	global_load_ushort v88, v[14:15], off
	v_lshl_add_u64 v[14:15], v[14:15], 0, s[98:99]
	global_load_ushort v89, v[14:15], off
	v_lshl_add_u64 v[14:15], v[14:15], 0, s[98:99]
	global_load_ushort v90, v[14:15], off
	v_lshl_add_u64 v[14:15], v[14:15], 0, s[98:99]
	global_load_ushort v91, v[14:15], off
	v_lshl_add_u64 v[14:15], v[14:15], 0, s[98:99]
	global_load_ushort v92, v[14:15], off
	v_lshl_add_u64 v[14:15], v[14:15], 0, s[98:99]
	global_load_ushort v93, v[14:15], off
	v_lshl_add_u64 v[14:15], v[14:15], 0, s[98:99]
	global_load_ushort v94, v[14:15], off
	v_cmp_lt_i32_e32 vcc, 0, v12
	s_waitcnt vmcnt(0)
	v_lshlrev_b32_e32 v11, 16, v84
	v_lshlrev_b32_e32 v0, 16, v85
	v_lshlrev_b32_e32 v14, 16, v86
	v_lshlrev_b32_e32 v13, 16, v87
	v_lshlrev_b32_e32 v16, 16, v88
	v_lshlrev_b32_e32 v15, 16, v89
	v_lshlrev_b32_e32 v33, 16, v90
	v_lshlrev_b32_e32 v17, 16, v91
	v_lshlrev_b32_e32 v36, 16, v92
	v_lshlrev_b32_e32 v35, 16, v93
	v_lshlrev_b32_e32 v12, 16, v94
	v_cndmask_b32_e32 v11, 0, v11, vcc
	v_cndmask_b32_e32 v0, 0, v0, vcc
	v_cndmask_b32_e32 v14, 0, v14, vcc
	v_fma_f32 v2, v7, v11, v9
	v_fmac_f32_e32 v2, v6, v0
	v_fmac_f32_e32 v2, v10, v14
	v_fma_f32 v0, v7, v0, v9
	v_fmac_f32_e32 v2, v8, v13
	v_add_u32_e32 v3, v57, v59
	v_fmac_f32_e32 v0, v6, v14
	ds_write_b32 v3, v2
	v_bfe_u32 v3, v2, 16, 1
	v_fmac_f32_e32 v0, v10, v13
	v_add3_u32 v2, v2, v3, s78
	v_fmac_f32_e32 v0, v8, v16
	ds_write_b16_d16_hi v62, v2 offset:16384
	v_bfe_u32 v2, v0, 16, 1
	ds_write_b32 v63, v0
	v_add3_u32 v0, v0, v2, s78
	ds_write_b16_d16_hi v62, v0 offset:16528
	v_fma_f32 v0, v7, v14, v9
	v_fmac_f32_e32 v0, v6, v13
	v_fmac_f32_e32 v0, v10, v16
	v_fmac_f32_e32 v0, v8, v15
	v_bfe_u32 v2, v0, 16, 1
	ds_write_b32 v64, v0
	v_add3_u32 v0, v0, v2, s78
	ds_write_b16_d16_hi v62, v0 offset:16672
	v_fma_f32 v0, v7, v13, v9
	v_fmac_f32_e32 v0, v6, v16
	v_fmac_f32_e32 v0, v10, v15
	v_fmac_f32_e32 v0, v8, v33
	v_bfe_u32 v2, v0, 16, 1
	ds_write_b32 v65, v0
	v_add3_u32 v0, v0, v2, s78
	ds_write_b16_d16_hi v62, v0 offset:16816
	v_fma_f32 v0, v7, v16, v9
	v_fmac_f32_e32 v0, v6, v15
	v_fmac_f32_e32 v0, v10, v33
	v_fmac_f32_e32 v0, v8, v17
	v_bfe_u32 v2, v0, 16, 1
	ds_write_b32 v66, v0
	v_add3_u32 v0, v0, v2, s78
	ds_write_b16_d16_hi v62, v0 offset:16960
	v_fma_f32 v0, v7, v15, v9
	v_fmac_f32_e32 v0, v6, v33
	v_fmac_f32_e32 v0, v10, v17
	v_fmac_f32_e32 v0, v8, v36
	v_bfe_u32 v2, v0, 16, 1
	ds_write_b32 v67, v0
	v_add3_u32 v0, v0, v2, s78
	ds_write_b16_d16_hi v62, v0 offset:17104
	v_fma_f32 v0, v7, v33, v9
	v_fmac_f32_e32 v0, v6, v17
	v_fmac_f32_e32 v0, v10, v36
	v_fmac_f32_e32 v9, v7, v17
	v_fmac_f32_e32 v0, v8, v35
	v_fmac_f32_e32 v9, v6, v36
	v_bfe_u32 v2, v0, 16, 1
	v_fmac_f32_e32 v9, v10, v35
	ds_write_b32 v68, v0
	v_add3_u32 v0, v0, v2, s78
	v_fmac_f32_e32 v9, v8, v12
	s_lshl_b32 s72, s24, 13
	ds_write_b16_d16_hi v62, v0 offset:17248
	v_bfe_u32 v0, v9, 16, 1
	v_lshl_add_u64 v[36:37], v[20:21], 0, s[72:73]
	v_mov_b32_e32 v33, v1
	v_add3_u32 v0, v9, v0, s78
	v_lshl_add_u64 v[40:41], v[36:37], 0, v[32:33]
	ds_write_b32 v69, v9
	ds_write_b16_d16_hi v70, v0 offset:16384
	s_waitcnt lgkmcnt(0)
	s_barrier
	global_load_dwordx4 v[6:9], v[40:41], off
	ds_read_b128 v[2:5], v58 offset:16384
	v_lshl_add_u64 v[38:39], v[22:23], 0, s[72:73]
	v_lshl_add_u64 v[44:45], v[38:39], 0, v[32:33]
	s_cmp_lg_u32 s25, 0
	s_cselect_b64 s[24:25], -1, 0
	v_mov_b32_e32 v75, 1.0
	s_or_b64 s[24:25], s[24:25], s[20:21]
	s_waitcnt vmcnt(0) lgkmcnt(0)
	v_mfma_f32_16x16x32_bf16 v[10:13], v[2:5], v[6:9], 0
	global_load_dwordx4 v[6:9], v[44:45], off
	s_nop 0
	global_load_dwordx4 v[40:43], v[40:41], off offset:64
	s_waitcnt vmcnt(1)
	v_mfma_f32_16x16x32_bf16 v[14:17], v[2:5], v[6:9], 0
	ds_read_b128 v[6:9], v58 offset:16448
	s_waitcnt vmcnt(0) lgkmcnt(0)
	v_mfma_f32_16x16x32_bf16 v[10:13], v[6:9], v[40:43], v[10:13]
	global_load_dwordx4 v[40:43], v[44:45], off offset:64
	s_waitcnt vmcnt(0)
	v_mfma_f32_16x16x32_bf16 v[14:17], v[6:9], v[40:43], v[14:17]
	v_add_u32_e32 v40, s30, v60
	v_add_u32_e32 v0, s70, v40
	v_lshlrev_b64 v[42:43], 2, v[0:1]
	v_lshl_add_u64 v[44:45], s[16:17], 0, v[42:43]
	global_load_dword v35, v[44:45], off
	v_lshl_add_u64 v[44:45], s[8:9], 0, v[42:43]
	v_lshl_add_u64 v[42:43], s[10:11], 0, v[42:43]
	global_load_dword v0, v[42:43], off
	global_load_dword v55, v[44:45], off
	v_mov_b32_e32 v42, 0xff800000
	v_mov_b32_e32 v43, 1.0
	s_waitcnt vmcnt(1)
	v_max_f32_e64 v33, -v0, -v0
	v_mul_f32_e64 v0, |v0|, s82
	v_exp_f32_e32 v0, v0
	v_max_f32_e32 v33, 0, v33
	v_add_f32_e32 v0, 1.0, v0
	v_cmp_gt_f32_e32 vcc, s74, v0
	s_nop 1
	v_cndmask_b32_e64 v41, 0, 32, vcc
	v_ldexp_f32 v0, v0, v41
	v_log_f32_e32 v0, v0
	s_nop 0
	v_mul_f32_e32 v41, 0x3f317217, v0
	v_fma_f32 v41, v0, s83, -v41
	v_fmac_f32_e32 v41, 0x3377d1cf, v0
	v_fmac_f32_e32 v41, 0x3f317217, v0
	v_cmp_lt_f32_e64 s[4:5], |v0|, s92
	s_nop 1
	v_cndmask_b32_e64 v0, v0, v41, s[4:5]
	v_cndmask_b32_e32 v41, 0, v176, vcc
	v_sub_f32_e32 v0, v0, v41
	v_add_f32_e32 v54, v33, v0
	v_mov_b32_e32 v33, 0xff800000
	s_and_saveexec_b64 s[26:27], s[24:25]
	s_cbranch_execz .LBB0_367
	v_add_f32_e32 v0, v10, v35
	v_mul_f32_e32 v0, 0xbfb8aa3b, v0
	v_exp_f32_e32 v0, v0
	s_nop 0
	v_add_f32_e32 v0, 1.0, v0
	v_rcp_f32_e32 v0, v0
	s_nop 0
	v_mul_f32_e32 v0, 0xc1000000, v0
	v_mul_f32_e32 v42, v0, v54
	v_add_f32_e32 v0, v42, v42
	v_mul_f32_e32 v10, 0x3fb8aa3b, v0
	v_rndne_f32_e32 v10, v10
	v_fmamk_f32 v41, v10, 0xbf317218, v0
	v_fmac_f32_e32 v41, 0x3102e308, v10
	v_fmamk_f32 v43, v41, 0x395133b1, v171
	v_cmp_eq_f32_e32 vcc, s2, v10
	v_cvt_i32_f32_e32 v10, v10
	v_fmaak_f32 v43, v41, v43, 0x3c0887f9
	v_fmaak_f32 v43, v41, v43, 0x3d2aaa81
	v_fmaak_f32 v43, v41, v43, 0x3e2aaaab
	v_fma_f32 v43, v41, v43, 0.5
	v_ldexp_f32 v10, 1.0, v10
	v_mul_f32_e32 v43, v41, v43
	v_cndmask_b32_e32 v10, v10, v178, vcc
	v_fmac_f32_e32 v41, v41, v43
	v_add_f32_e32 v43, -1.0, v10
	v_fmac_f32_e32 v43, v10, v41
	v_add_f32_e32 v10, v43, v43
	v_cndmask_b32_e32 v10, v43, v10, vcc
	v_max_f32_e64 v10, -v10, 0
	v_cmp_gt_f32_e32 vcc, s93, v10
	v_mul_f32_e32 v41, 0x4f800000, v10
	s_nop 0
	v_cndmask_b32_e32 v10, v10, v41, vcc
	v_sqrt_f32_e32 v41, v10
	s_nop 0
	v_add_u32_e32 v43, -1, v41
	v_fma_f32 v44, -v43, v41, v10
	v_cmp_ge_f32_e64 s[4:5], 0, v44
	v_add_u32_e32 v44, 1, v41
	s_nop 0
	v_cndmask_b32_e64 v43, v41, v43, s[4:5]
	v_fma_f32 v41, -v44, v41, v10
	v_cmp_lt_f32_e64 s[4:5], 0, v41
	s_nop 1
	v_cndmask_b32_e64 v41, v43, v44, s[4:5]
	v_mul_f32_e32 v43, 0x37800000, v41
	v_cndmask_b32_e32 v41, v41, v43, vcc
	v_cmp_class_f32_e32 vcc, v10, v170
	s_nop 1
	v_cndmask_b32_e32 v10, v41, v10, vcc
	v_cmp_nlt_f32_e32 vcc, s3, v0
	s_nop 1
	v_cndmask_b32_e32 v10, 0, v10, vcc
	v_cmp_ngt_f32_e32 vcc, s52, v0
	s_nop 1
	v_cndmask_b32_e32 v43, 1.0, v10, vcc

.LBB0_481:
	s_xor_b64 s[18:19], s[36:37], -1
	s_mov_b64 s[0:1], -1
	s_mov_b64 s[20:21], 0
	s_cmp_lt_i32 s58, 2
	s_mov_b64 s[4:5], 0
	s_cbranch_scc1 .LBB0_574
	s_cmp_gt_i32 s58, 3
	s_mov_b64 s[4:5], -1
	s_cbranch_scc0 .LBB0_496
	v_readlane_b32 s0, v251, 21
	v_mov_b32_e32 v0, v162
	v_readlane_b32 s1, v251, 22
	s_ashr_i32 s31, s30, 31
	v_add_u32_e32 v36, s0, v0
	v_readlane_b32 s0, v252, 0
	v_readlane_b32 s1, v252, 1
	s_load_dwordx2 s[6:7], s[0:1], 0x158
	v_ashrrev_i32_e32 v2, 6, v36
	s_lshl_b64 s[4:5], s[30:31], 21
	v_ashrrev_i32_e32 v3, 31, v2
	v_lshlrev_b64 v[6:7], 18, v[2:3]
	s_waitcnt lgkmcnt(0)
	s_add_u32 s4, s6, s4
	s_addc_u32 s5, s7, s5
	v_lshl_add_u64 v[6:7], s[4:5], 0, v[6:7]
	s_mul_i32 s4, s30, 0x600000
	s_mul_hi_i32 s5, s30, 0x600000
	s_add_u32 s4, s6, s4
	s_addc_u32 s5, s7, s5
	v_and_b32_e32 v18, 63, v0
	v_mov_b64_e32 v[8:9], s[4:5]
	s_mov_b32 s4, 0xc0000
	v_lshl_or_b32 v0, s34, 6, v18
	v_mad_i64_i32 v[8:9], s[4:5], v2, s4, v[8:9]
	v_lshlrev_b32_e32 v4, 1, v0
	v_mov_b32_e32 v5, v1
	v_mov_b32_e32 v15, 1.0
	v_mov_b32_e32 v16, 0
	s_mov_b32 s4, -16
	v_mov_b64_e32 v[10:11], v[8:9]
	v_mov_b64_e32 v[12:13], v[6:7]
	s_mov_b32 s5, 0xe8c1000
	s_mov_b32 s8, 0xe8c2000
	s_mov_b32 s9, 0x1c609000
	s_mov_b32 s10, 0xe8c3000
	s_mov_b32 s11, 0xe8c4000
	s_mov_b32 s12, 0xe8c5000
	s_mov_b32 s13, 0x1c60a000
	s_mov_b32 s14, 0xe8c6000
	s_mov_b32 s15, 0xe8c7000
	s_mov_b32 s16, 0xe8c8000
	s_mov_b32 s17, 0x1c60b000
	s_mov_b32 s22, 0xe8c9000
	s_mov_b32 s23, 0xe8ca000
	s_mov_b32 s24, 0xe8cb000
	s_mov_b64 s[26:27], 0x4000
	s_mov_b64 s[38:39], 0xc000
	v_lshl_add_u64 v[12:13], v[12:13], 0, v[4:5]
	v_lshl_add_u64 v[10:11], v[10:11], 0, v[4:5]
	s_mov_b32 s8, 0x1c608000
	s_mov_b32 s9, 0
	v_lshl_add_u64 v[12:13], v[12:13], 0, s[8:9]
	s_mov_b32 s8, s81
	v_lshl_add_u64 v[10:11], v[10:11], 0, s[8:9]
	s_movk_i32 s26, 0x400
	s_mov_b32 s27, 0
	s_movk_i32 s38, 0xc00
	s_mov_b32 s39, 0
	s_mov_b32 s4, 0
	global_load_ushort v48, v[12:13], off
	v_lshl_add_u64 v[12:13], v[12:13], 0, s[26:27]
	global_load_ushort v49, v[12:13], off
	v_lshl_add_u64 v[12:13], v[12:13], 0, s[26:27]
	global_load_ushort v50, v[12:13], off
	v_lshl_add_u64 v[12:13], v[12:13], 0, s[26:27]
	global_load_ushort v51, v[12:13], off
	v_lshl_add_u64 v[12:13], v[12:13], 0, s[26:27]
	global_load_ushort v52, v[12:13], off
	v_lshl_add_u64 v[12:13], v[12:13], 0, s[26:27]
	global_load_ushort v53, v[12:13], off
	v_lshl_add_u64 v[12:13], v[12:13], 0, s[26:27]
	global_load_ushort v54, v[12:13], off
	v_lshl_add_u64 v[12:13], v[12:13], 0, s[26:27]
	global_load_ushort v55, v[12:13], off
	v_lshl_add_u64 v[12:13], v[12:13], 0, s[26:27]
	global_load_ushort v56, v[12:13], off
	v_lshl_add_u64 v[12:13], v[12:13], 0, s[26:27]
	global_load_ushort v57, v[12:13], off
	v_lshl_add_u64 v[12:13], v[12:13], 0, s[26:27]
	global_load_ushort v58, v[12:13], off
	v_lshl_add_u64 v[12:13], v[12:13], 0, s[26:27]
	global_load_ushort v59, v[12:13], off
	v_lshl_add_u64 v[12:13], v[12:13], 0, s[26:27]
	global_load_ushort v60, v[12:13], off
	v_lshl_add_u64 v[12:13], v[12:13], 0, s[26:27]
	global_load_ushort v61, v[12:13], off
	v_lshl_add_u64 v[12:13], v[12:13], 0, s[26:27]
	global_load_ushort v62, v[12:13], off
	v_lshl_add_u64 v[12:13], v[12:13], 0, s[26:27]
	global_load_ushort v63, v[12:13], off
	v_lshl_add_u64 v[12:13], v[12:13], 0, s[26:27]
	global_load_ushort v64, v[10:11], off
	v_lshl_add_u64 v[10:11], v[10:11], 0, s[38:39]
	global_load_ushort v65, v[10:11], off
	v_lshl_add_u64 v[10:11], v[10:11], 0, s[38:39]
	global_load_ushort v66, v[10:11], off
	v_lshl_add_u64 v[10:11], v[10:11], 0, s[38:39]
	global_load_ushort v67, v[10:11], off
	v_lshl_add_u64 v[10:11], v[10:11], 0, s[38:39]
	global_load_ushort v68, v[10:11], off
	v_lshl_add_u64 v[10:11], v[10:11], 0, s[38:39]
	global_load_ushort v69, v[10:11], off
	v_lshl_add_u64 v[10:11], v[10:11], 0, s[38:39]
	global_load_ushort v70, v[10:11], off
	v_lshl_add_u64 v[10:11], v[10:11], 0, s[38:39]
	global_load_ushort v71, v[10:11], off
	v_lshl_add_u64 v[10:11], v[10:11], 0, s[38:39]
	global_load_ushort v72, v[10:11], off
	v_lshl_add_u64 v[10:11], v[10:11], 0, s[38:39]
	global_load_ushort v73, v[10:11], off
	v_lshl_add_u64 v[10:11], v[10:11], 0, s[38:39]
	global_load_ushort v74, v[10:11], off
	v_lshl_add_u64 v[10:11], v[10:11], 0, s[38:39]
	global_load_ushort v75, v[10:11], off
	v_lshl_add_u64 v[10:11], v[10:11], 0, s[38:39]
	global_load_ushort v76, v[10:11], off
	v_lshl_add_u64 v[10:11], v[10:11], 0, s[38:39]
	global_load_ushort v77, v[10:11], off
	v_lshl_add_u64 v[10:11], v[10:11], 0, s[38:39]
	global_load_ushort v78, v[10:11], off
	v_lshl_add_u64 v[10:11], v[10:11], 0, s[38:39]
	global_load_ushort v79, v[10:11], off
	v_lshl_add_u64 v[10:11], v[10:11], 0, s[38:39]
.Llq1_loop:
	s_waitcnt vmcnt(0)
	v_lshlrev_b32_e32 v20, 16, v48
	v_lshlrev_b32_e32 v38, 16, v64
	v_lshlrev_b32_e32 v21, 16, v49
	v_lshlrev_b32_e32 v39, 16, v65
	v_lshlrev_b32_e32 v22, 16, v50
	v_lshlrev_b32_e32 v40, 16, v66
	v_lshlrev_b32_e32 v23, 16, v51
	v_lshlrev_b32_e32 v41, 16, v67
	v_lshlrev_b32_e32 v24, 16, v52
	v_lshlrev_b32_e32 v42, 16, v68
	v_lshlrev_b32_e32 v25, 16, v53
	v_lshlrev_b32_e32 v43, 16, v69
	v_lshlrev_b32_e32 v26, 16, v54
	v_lshlrev_b32_e32 v44, 16, v70
	v_lshlrev_b32_e32 v27, 16, v55
	v_lshlrev_b32_e32 v45, 16, v71
	v_lshlrev_b32_e32 v28, 16, v56
	v_lshlrev_b32_e32 v46, 16, v72
	v_lshlrev_b32_e32 v29, 16, v57
	v_lshlrev_b32_e32 v47, 16, v73
	v_lshlrev_b32_e32 v30, 16, v58
	v_lshlrev_b32_e32 v80, 16, v74
	v_lshlrev_b32_e32 v31, 16, v59
	v_lshlrev_b32_e32 v81, 16, v75
	v_lshlrev_b32_e32 v32, 16, v60
	v_lshlrev_b32_e32 v82, 16, v76
	v_lshlrev_b32_e32 v33, 16, v61
	v_lshlrev_b32_e32 v83, 16, v77
	v_lshlrev_b32_e32 v34, 16, v62
	v_lshlrev_b32_e32 v84, 16, v78
	v_lshlrev_b32_e32 v35, 16, v63
	v_lshlrev_b32_e32 v85, 16, v79
	v_mul_f32_e32 v20, 0x3fb8aa3b, v20
	v_mul_f32_e32 v21, 0x3fb8aa3b, v21
	v_mul_f32_e32 v22, 0x3fb8aa3b, v22
	v_mul_f32_e32 v23, 0x3fb8aa3b, v23
	v_mul_f32_e32 v24, 0x3fb8aa3b, v24
	v_mul_f32_e32 v25, 0x3fb8aa3b, v25
	v_mul_f32_e32 v26, 0x3fb8aa3b, v26
	v_mul_f32_e32 v27, 0x3fb8aa3b, v27
	v_mul_f32_e32 v28, 0x3fb8aa3b, v28
	v_mul_f32_e32 v29, 0x3fb8aa3b, v29
	v_mul_f32_e32 v30, 0x3fb8aa3b, v30
	v_mul_f32_e32 v31, 0x3fb8aa3b, v31
	v_mul_f32_e32 v32, 0x3fb8aa3b, v32
	v_mul_f32_e32 v33, 0x3fb8aa3b, v33
	v_mul_f32_e32 v34, 0x3fb8aa3b, v34
	v_mul_f32_e32 v35, 0x3fb8aa3b, v35
	v_exp_f32_e32 v20, v20
	v_exp_f32_e32 v21, v21
	v_exp_f32_e32 v22, v22
	v_exp_f32_e32 v23, v23
	v_exp_f32_e32 v24, v24
	v_exp_f32_e32 v25, v25
	v_exp_f32_e32 v26, v26
	v_exp_f32_e32 v27, v27
	v_exp_f32_e32 v28, v28
	v_exp_f32_e32 v29, v29
	v_exp_f32_e32 v30, v30
	v_exp_f32_e32 v31, v31
	v_exp_f32_e32 v32, v32
	v_exp_f32_e32 v33, v33
	v_exp_f32_e32 v34, v34
	v_exp_f32_e32 v35, v35
	s_add_i32 s4, s4, 1
	s_cmp_lt_u32 s4, 16
	s_cbranch_scc0 .Llq1_chain
	global_load_ushort v48, v[12:13], off
	v_lshl_add_u64 v[12:13], v[12:13], 0, s[26:27]
	global_load_ushort v49, v[12:13], off
	v_lshl_add_u64 v[12:13], v[12:13], 0, s[26:27]
	global_load_ushort v50, v[12:13], off
	v_lshl_add_u64 v[12:13], v[12:13], 0, s[26:27]
	global_load_ushort v51, v[12:13], off
	v_lshl_add_u64 v[12:13], v[12:13], 0, s[26:27]
	global_load_ushort v52, v[12:13], off
	v_lshl_add_u64 v[12:13], v[12:13], 0, s[26:27]
	global_load_ushort v53, v[12:13], off
	v_lshl_add_u64 v[12:13], v[12:13], 0, s[26:27]
	global_load_ushort v54, v[12:13], off
	v_lshl_add_u64 v[12:13], v[12:13], 0, s[26:27]
	global_load_ushort v55, v[12:13], off
	v_lshl_add_u64 v[12:13], v[12:13], 0, s[26:27]
	global_load_ushort v56, v[12:13], off
	v_lshl_add_u64 v[12:13], v[12:13], 0, s[26:27]
	global_load_ushort v57, v[12:13], off
	v_lshl_add_u64 v[12:13], v[12:13], 0, s[26:27]
	global_load_ushort v58, v[12:13], off
	v_lshl_add_u64 v[12:13], v[12:13], 0, s[26:27]
	global_load_ushort v59, v[12:13], off
	v_lshl_add_u64 v[12:13], v[12:13], 0, s[26:27]
	global_load_ushort v60, v[12:13], off
	v_lshl_add_u64 v[12:13], v[12:13], 0, s[26:27]
	global_load_ushort v61, v[12:13], off
	v_lshl_add_u64 v[12:13], v[12:13], 0, s[26:27]
	global_load_ushort v62, v[12:13], off
	v_lshl_add_u64 v[12:13], v[12:13], 0, s[26:27]
	global_load_ushort v63, v[12:13], off
	v_lshl_add_u64 v[12:13], v[12:13], 0, s[26:27]
	global_load_ushort v64, v[10:11], off
	v_lshl_add_u64 v[10:11], v[10:11], 0, s[38:39]
	global_load_ushort v65, v[10:11], off
	v_lshl_add_u64 v[10:11], v[10:11], 0, s[38:39]
	global_load_ushort v66, v[10:11], off
	v_lshl_add_u64 v[10:11], v[10:11], 0, s[38:39]
	global_load_ushort v67, v[10:11], off
	v_lshl_add_u64 v[10:11], v[10:11], 0, s[38:39]
	global_load_ushort v68, v[10:11], off
	v_lshl_add_u64 v[10:11], v[10:11], 0, s[38:39]
	global_load_ushort v69, v[10:11], off
	v_lshl_add_u64 v[10:11], v[10:11], 0, s[38:39]
	global_load_ushort v70, v[10:11], off
	v_lshl_add_u64 v[10:11], v[10:11], 0, s[38:39]
	global_load_ushort v71, v[10:11], off
	v_lshl_add_u64 v[10:11], v[10:11], 0, s[38:39]
	global_load_ushort v72, v[10:11], off
	v_lshl_add_u64 v[10:11], v[10:11], 0, s[38:39]
	global_load_ushort v73, v[10:11], off
	v_lshl_add_u64 v[10:11], v[10:11], 0, s[38:39]
	global_load_ushort v74, v[10:11], off
	v_lshl_add_u64 v[10:11], v[10:11], 0, s[38:39]
	global_load_ushort v75, v[10:11], off
	v_lshl_add_u64 v[10:11], v[10:11], 0, s[38:39]
	global_load_ushort v76, v[10:11], off
	v_lshl_add_u64 v[10:11], v[10:11], 0, s[38:39]
	global_load_ushort v77, v[10:11], off
	v_lshl_add_u64 v[10:11], v[10:11], 0, s[38:39]
	global_load_ushort v78, v[10:11], off
	v_lshl_add_u64 v[10:11], v[10:11], 0, s[38:39]
	global_load_ushort v79, v[10:11], off
	v_lshl_add_u64 v[10:11], v[10:11], 0, s[38:39]
.Llq1_chain:
	v_fma_f32 v16, v20, v16, v38
	v_mul_f32_e32 v15, v15, v20
	v_fma_f32 v16, v21, v16, v39
	v_mul_f32_e32 v15, v15, v21
	v_fma_f32 v16, v22, v16, v40
	v_mul_f32_e32 v15, v15, v22
	v_fma_f32 v16, v23, v16, v41
	v_mul_f32_e32 v15, v15, v23
	v_fma_f32 v16, v24, v16, v42
	v_mul_f32_e32 v15, v15, v24
	v_fma_f32 v16, v25, v16, v43
	v_mul_f32_e32 v15, v15, v25
	v_fma_f32 v16, v26, v16, v44
	v_mul_f32_e32 v15, v15, v26
	v_fma_f32 v16, v27, v16, v45
	v_mul_f32_e32 v15, v15, v27
	v_fma_f32 v16, v28, v16, v46
	v_mul_f32_e32 v15, v15, v28
	v_fma_f32 v16, v29, v16, v47
	v_mul_f32_e32 v15, v15, v29
	v_fma_f32 v16, v30, v16, v80
	v_mul_f32_e32 v15, v15, v30
	v_fma_f32 v16, v31, v16, v81
	v_mul_f32_e32 v15, v15, v31
	v_fma_f32 v16, v32, v16, v82
	v_mul_f32_e32 v15, v15, v32
	v_fma_f32 v16, v33, v16, v83
	v_mul_f32_e32 v15, v15, v33
	v_fma_f32 v16, v34, v16, v84
	v_mul_f32_e32 v15, v15, v34
	v_fma_f32 v16, v35, v16, v85
	v_mul_f32_e32 v15, v15, v35
	s_cmp_lt_u32 s4, 16
	s_cbranch_scc1 .Llq1_loop
	v_lshl_add_u32 v10, v36, 2, 0
	v_cmp_lt_i32_e32 vcc, 0, v2
	v_mov_b32_e32 v12, 0
	s_barrier
	ds_write2st64_b32 v10, v15, v16 offset1:8
	s_waitcnt lgkmcnt(0)
	s_barrier
	s_and_saveexec_b64 s[4:5], vcc
	s_cbranch_execz .LBB0_489
	v_lshl_add_u32 v10, v18, 2, 0
	v_mov_b32_e32 v12, 0
	s_mov_b64 s[8:9], 0
	v_mov_b32_e32 v11, v2

.LBB0_606:
	s_and_b64 s[20:21], s[36:37], exec
	s_cselect_b32 s20, s65, s28
	v_lshl_add_u32 v112, s20, 5, v81
	s_waitcnt lgkmcnt(0)
	v_cndmask_b32_e64 v0, 0, 1, s[36:37]
	v_cmp_ne_u32_e64 s[20:21], 1, v0
	s_andn2_b64 vcc, exec, s[36:37]
	v_ashrrev_i32_e32 v113, 31, v112
	s_cbranch_vccnz .LBB0_608
	s_load_dwordx2 s[58:59], s[22:23], 0x38
	v_lshlrev_b64 v[32:33], 8, v[112:113]
	v_lshlrev_b32_e32 v0, 2, v84
	s_waitcnt lgkmcnt(0)
	s_add_u32 s58, s58, s62
	s_addc_u32 s59, s59, s63
	v_lshl_add_u64 v[32:33], s[58:59], 0, v[32:33]
	v_lshl_add_u64 v[36:37], v[32:33], 0, v[0:1]
	global_load_dwordx4 v[32:35], v[36:37], off offset:16
	s_nop 0
	global_load_dwordx4 v[36:39], v[36:37], off
	s_waitcnt vmcnt(0)

.LBB0_609:
	ds_read_b128 v[144:147], v137
	ds_read_b128 v[148:151], v137 offset:16
	ds_read_b128 v[152:155], v137 offset:256
	ds_read_b128 v[156:159], v137 offset:272
	ds_read_b128 v[182:185], v137 offset:512
	ds_read_b128 v[186:189], v137 offset:528
	ds_read_b128 v[190:193], v137 offset:768
	ds_read_b128 v[194:197], v137 offset:784
	ds_read_b128 v[198:201], v137 offset:1024
	ds_read_b128 v[202:205], v137 offset:1040
	ds_read_b32 v160, v136
	s_add_i32 s59, s58, 1
	s_waitcnt lgkmcnt(14)
	v_pk_mul_f32 v[78:79], v[34:35], v[78:79]
	v_pk_mul_f32 v[76:77], v[32:33], v[76:77]
	v_pk_fma_f32 v[74:75], v[38:39], v[74:75], v[78:79]
	v_pk_fma_f32 v[72:73], v[36:37], v[72:73], v[76:77]
	s_and_b32 s70, s58, 6
	v_pk_mov_b32 v[76:77], v[72:73], v[74:75] op_sel:[1,0]
	v_mov_b32_e32 v73, v75
	v_pk_add_f32 v[72:73], v[76:77], v[72:73]
	v_cmp_eq_u32_e32 vcc, s70, v86
	v_add_f32_e32 v72, v72, v73
	s_add_i32 s89, s58, 2
	s_cmp_lt_u32 s58, 30
	v_add_f32_dpp v72, v72, v72 quad_perm:[1,0,3,2] row_mask:0xf bank_mask:0xf bound_ctrl:1
	s_cselect_b32 s70, s95, 0x2e80
	s_lshl_b32 s70, s70, 2
	v_add_f32_dpp v72, v72, v72 quad_perm:[2,3,0,1] row_mask:0xf bank_mask:0xf bound_ctrl:1
	s_and_b32 s59, s59, 7
	s_nop 0
	v_add_f32_dpp v72, v72, v72 row_half_mirror row_mask:0xf bank_mask:0xf bound_ctrl:1
	v_pk_mul_f32 v[68:69], v[68:69], v[72:73] op_sel_hi:[1,0]
	v_pk_mul_f32 v[70:71], v[70:71], v[72:73] op_sel_hi:[1,0]
	s_waitcnt lgkmcnt(11)
	v_pk_fma_f32 v[64:65], v[64:65], v[0:1], v[68:69] op_sel_hi:[1,0,1] neg_lo:[0,0,1] neg_hi:[0,0,1]
	v_pk_fma_f32 v[66:67], v[66:67], v[0:1], v[70:71] op_sel_hi:[1,0,1] neg_lo:[0,0,1] neg_hi:[0,0,1]
	v_pk_fma_f32 v[36:37], v[36:37], v[48:49], v[64:65]
	v_pk_fma_f32 v[38:39], v[38:39], v[50:51], v[66:67]
	v_pk_mul_f32 v[48:49], v[58:59], v[72:73] op_sel_hi:[1,0]
	v_pk_mul_f32 v[50:51], v[56:57], v[72:73] op_sel_hi:[1,0]
	v_pk_fma_f32 v[48:49], v[62:63], v[0:1], v[48:49] op_sel_hi:[1,0,1] neg_lo:[0,0,1] neg_hi:[0,0,1]
	v_pk_fma_f32 v[50:51], v[60:61], v[0:1], v[50:51] op_sel_hi:[1,0,1] neg_lo:[0,0,1] neg_hi:[0,0,1]
	v_pk_fma_f32 v[34:35], v[34:35], v[42:43], v[48:49]
	v_pk_fma_f32 v[32:33], v[32:33], v[40:41], v[50:51]
	v_pk_mul_f32 v[42:43], v[54:55], v[34:35]
	v_pk_mul_f32 v[40:41], v[52:53], v[32:33]
	v_pk_fma_f32 v[42:43], v[46:47], v[38:39], v[42:43]
	v_pk_fma_f32 v[40:41], v[44:45], v[36:37], v[40:41]
	s_nop 0
	v_pk_mov_b32 v[44:45], v[40:41], v[42:43] op_sel:[1,0]
	v_mov_b32_e32 v41, v43
	v_pk_add_f32 v[40:41], v[44:45], v[40:41]
	s_nop 0
	v_add_f32_e32 v0, v40, v41
	s_nop 1
	v_add_f32_dpp v0, v0, v0 quad_perm:[1,0,3,2] row_mask:0xf bank_mask:0xf bound_ctrl:1
	s_nop 1
	v_add_f32_dpp v0, v0, v0 quad_perm:[2,3,0,1] row_mask:0xf bank_mask:0xf bound_ctrl:1
	s_nop 1
	v_add_f32_dpp v0, v0, v0 row_half_mirror row_mask:0xf bank_mask:0xf bound_ctrl:1
	v_cndmask_b32_e32 v161, v142, v0, vcc
	s_waitcnt lgkmcnt(7)
	v_pk_mul_f32 v[142:143], v[156:157], v[32:33]
	v_pk_mul_f32 v[156:157], v[158:159], v[34:35]
	v_pk_fma_f32 v[142:143], v[152:153], v[36:37], v[142:143]
	v_pk_fma_f32 v[154:155], v[154:155], v[38:39], v[156:157]
	v_add_u32_e32 v0, s70, v124
	v_pk_mov_b32 v[152:153], v[142:143], v[154:155] op_sel:[1,0]
	v_mov_b32_e32 v143, v155
	v_pk_add_f32 v[142:143], v[152:153], v[142:143]
	ds_read_b128 v[48:51], v0
	ds_read_b128 v[40:43], v0 offset:16
	ds_read_b128 v[72:75], v0 offset:256
	ds_read_b128 v[76:79], v0 offset:272
	ds_read_b128 v[68:71], v0 offset:512
	ds_read_b128 v[56:59], v0 offset:528
	ds_read_b128 v[64:67], v0 offset:768
	ds_read_b128 v[60:63], v0 offset:784
	ds_read_b128 v[44:47], v0 offset:1024
	ds_read_b128 v[52:55], v0 offset:1040
	v_add_f32_e32 v142, v142, v143
	v_add_u32_e32 v0, s70, v135
	ds_read_b32 v0, v0 offset:1280
	v_add_f32_dpp v142, v142, v142 quad_perm:[1,0,3,2] row_mask:0xf bank_mask:0xf bound_ctrl:1
	v_cmp_eq_u32_e32 vcc, s59, v86
	s_nop 0
	v_add_f32_dpp v142, v142, v142 quad_perm:[2,3,0,1] row_mask:0xf bank_mask:0xf bound_ctrl:1
	s_nop 1
	v_add_f32_dpp v142, v142, v142 row_half_mirror row_mask:0xf bank_mask:0xf bound_ctrl:1
	s_waitcnt lgkmcnt(14)
	v_pk_mul_f32 v[154:155], v[182:183], v[142:143] op_sel_hi:[1,0]
	v_pk_mul_f32 v[152:153], v[184:185], v[142:143] op_sel_hi:[1,0]
	s_waitcnt lgkmcnt(11)
	v_pk_fma_f32 v[154:155], v[190:191], v[160:161], v[154:155] op_sel_hi:[1,0,1] neg_lo:[0,0,1] neg_hi:[0,0,1]
	v_pk_fma_f32 v[152:153], v[192:193], v[160:161], v[152:153] op_sel_hi:[1,0,1] neg_lo:[0,0,1] neg_hi:[0,0,1]
	v_pk_fma_f32 v[36:37], v[144:145], v[36:37], v[154:155]
	v_pk_mul_f32 v[144:145], v[188:189], v[142:143] op_sel_hi:[1,0]
	v_pk_mul_f32 v[142:143], v[186:187], v[142:143] op_sel_hi:[1,0]
	v_pk_fma_f32 v[144:145], v[196:197], v[160:161], v[144:145] op_sel_hi:[1,0,1] neg_lo:[0,0,1] neg_hi:[0,0,1]
	v_pk_fma_f32 v[142:143], v[194:195], v[160:161], v[142:143] op_sel_hi:[1,0,1] neg_lo:[0,0,1] neg_hi:[0,0,1]
	v_pk_fma_f32 v[34:35], v[150:151], v[34:35], v[144:145]
	v_pk_fma_f32 v[32:33], v[148:149], v[32:33], v[142:143]
	v_pk_fma_f32 v[38:39], v[146:147], v[38:39], v[152:153]
	v_pk_mul_f32 v[142:143], v[202:203], v[32:33]
	v_pk_mul_f32 v[144:145], v[204:205], v[34:35]
	v_pk_fma_f32 v[142:143], v[198:199], v[36:37], v[142:143]
	v_pk_fma_f32 v[144:145], v[200:201], v[38:39], v[144:145]
	s_nop 0
	v_pk_mov_b32 v[146:147], v[142:143], v[144:145] op_sel:[1,0]
	v_mov_b32_e32 v143, v145
	v_pk_add_f32 v[142:143], v[146:147], v[142:143]
	s_nop 0
	v_add_f32_e32 v142, v142, v143
	s_nop 1
	v_add_f32_dpp v142, v142, v142 quad_perm:[1,0,3,2] row_mask:0xf bank_mask:0xf bound_ctrl:1
	s_nop 1
	v_add_f32_dpp v142, v142, v142 quad_perm:[2,3,0,1] row_mask:0xf bank_mask:0xf bound_ctrl:1
	s_nop 1
	v_add_f32_dpp v142, v142, v142 row_half_mirror row_mask:0xf bank_mask:0xf bound_ctrl:1
	v_cndmask_b32_e32 v142, v161, v142, vcc
	s_cmp_lg_u32 s59, 7
	s_cselect_b64 vcc, -1, 0
	s_cmp_ge_u32 s89, s85
	s_cselect_b64 s[70:71], -1, 0
	s_cmp_lt_u32 s89, s85
	s_cselect_b64 s[80:81], -1, 0
	s_and_b64 s[80:81], vcc, s[80:81]
	s_and_b64 vcc, exec, s[80:81]
	s_cbranch_vccnz .LBB0_619
	s_cmp_lt_u32 s58, 8
	s_cbranch_scc1 .LBB0_617
	s_lshr_b32 s58, s58, 3
	s_cmp_lt_i32 s58, 2
	s_cbranch_scc1 .LBB0_618
	s_cmp_lg_u32 s58, 2
	s_mov_b64 s[58:59], -1
	s_cbranch_scc0 .LBB0_614
	s_mov_b64 s[58:59], 0
